# g12 + nt (streaming) policy on P8 ACT output stores
# speedup vs baseline: 1.0009x; 1.0009x over previous
; DI int tidx() { int t = __builtin_amdgcn_workitem_id_x(); asm volatile("" : "+v"(t)); return t; }
; DI void phase8(const Params& p, const Sched& sched, unsigned char* smem) {
;     ...
;       __syncthreads();
;       const int tid = tidx(), F0 = tn * 64;
; #pragma unroll
;       for (int i = 0; i < 8; ++i) {
;         const int c = tid + 256 * i, fblk = c >> 10, row = (c & 1023) >> 2, ch = (c & 3) * 8;
;         if (row >= 2) *(u32x4*)(act + ((size_t)((F0 >> 5) + fblk) * Tn + (size_t)tm * 256 + row) * 32 + ch) = *(const u32x4*)(Ls + row * 72 + fblk * 32 + ch);
;       }
.LBB0_958:
	s_or_b64 exec, exec, s[4:5]
	s_nop 0
	v_mov_b32_e32 v0, v218
	s_waitcnt lgkmcnt(0)
	s_barrier
	s_lshl_b32 s34, s56, 1
	v_lshlrev_b32_e32 v1, 3, v0
	v_and_b32_e32 v3, 24, v1
	v_bfe_u32 v1, v0, 2, 8
	v_cmp_lt_u32_e32 vcc, 1, v1
	v_mul_u32_u24_e32 v2, 0x90, v1
	v_lshlrev_b32_e32 v152, 1, v3
	s_and_saveexec_b64 s[4:5], vcc
	s_cbranch_execz .LBB0_960
	v_ashrrev_i32_e32 v3, 10, v0
	v_add_u32_e32 v8, s34, v3
	v_lshlrev_b32_e32 v4, 6, v3
	v_ashrrev_i32_e32 v9, 31, v8
	s_ashr_i32 s31, s30, 31
	v_add3_u32 v4, v2, v4, v152
	v_lshlrev_b64 v[8:9], 16, v[8:9]
	s_lshl_b64 s[6:7], s[30:31], 8
	ds_read_b128 v[4:7], v4 offset:36864
	v_lshl_add_u64 v[8:9], v[8:9], 0, s[6:7]
	v_or_b32_e32 v8, v8, v1
	v_lshlrev_b64 v[8:9], 6, v[8:9]
	v_lshl_add_u64 v[8:9], s[8:9], 0, v[8:9]
	v_lshl_add_u64 v[8:9], v[8:9], 0, v[152:153]
	s_waitcnt lgkmcnt(0)
	global_store_dwordx4 v[8:9], v[4:7], off nt
.LBB0_960:
	s_or_b64 exec, exec, s[4:5]
	s_nop 0
	v_add_u32_e32 v4, 0x100, v0
	v_bfe_u32 v3, v4, 2, 8
	v_cmp_lt_u32_e64 s[4:5], 1, v3
	s_and_saveexec_b64 s[6:7], s[4:5]
	s_cbranch_execz .LBB0_962
	v_ashrrev_i32_e32 v8, 10, v4
	v_lshlrev_b32_e32 v5, 6, v8
	v_add_u32_e32 v8, s34, v8
	v_mul_u32_u24_e32 v4, 0x90, v3
	v_ashrrev_i32_e32 v9, 31, v8
	s_ashr_i32 s31, s30, 31
	v_add3_u32 v4, v4, v5, v152
	v_lshlrev_b64 v[8:9], 16, v[8:9]
	s_lshl_b64 s[4:5], s[30:31], 8
	ds_read_b128 v[4:7], v4 offset:36864
	v_lshl_add_u64 v[8:9], v[8:9], 0, s[4:5]
	v_or_b32_e32 v8, v8, v3
	v_lshlrev_b64 v[8:9], 6, v[8:9]
	v_lshl_add_u64 v[8:9], s[8:9], 0, v[8:9]
	v_lshl_add_u64 v[8:9], v[8:9], 0, v[152:153]
	s_waitcnt lgkmcnt(0)
	global_store_dwordx4 v[8:9], v[4:7], off nt
.LBB0_962:
	s_or_b64 exec, exec, s[6:7]
	s_nop 0
	v_add_u32_e32 v4, 0x200, v0
	v_bfe_u32 v3, v4, 2, 8
	v_cmp_lt_u32_e64 s[4:5], 1, v3
	s_and_saveexec_b64 s[6:7], s[4:5]
	s_cbranch_execz .LBB0_964
	v_ashrrev_i32_e32 v8, 10, v4
	v_lshlrev_b32_e32 v5, 6, v8
	v_add_u32_e32 v8, s34, v8
	v_mul_u32_u24_e32 v4, 0x90, v3
	v_ashrrev_i32_e32 v9, 31, v8
	s_ashr_i32 s31, s30, 31
	v_add3_u32 v4, v4, v5, v152
	v_lshlrev_b64 v[8:9], 16, v[8:9]
	s_lshl_b64 s[4:5], s[30:31], 8
	ds_read_b128 v[4:7], v4 offset:36864
	v_lshl_add_u64 v[8:9], v[8:9], 0, s[4:5]
	v_or_b32_e32 v8, v8, v3
	v_lshlrev_b64 v[8:9], 6, v[8:9]
	v_lshl_add_u64 v[8:9], s[8:9], 0, v[8:9]
	v_lshl_add_u64 v[8:9], v[8:9], 0, v[152:153]
	s_waitcnt lgkmcnt(0)
	global_store_dwordx4 v[8:9], v[4:7], off nt
.LBB0_964:
	s_or_b64 exec, exec, s[6:7]
	s_nop 0
	v_add_u32_e32 v4, 0x300, v0
	v_bfe_u32 v3, v4, 2, 8
	v_cmp_lt_u32_e64 s[4:5], 1, v3
	s_and_saveexec_b64 s[6:7], s[4:5]
	s_cbranch_execz .LBB0_966
	v_ashrrev_i32_e32 v8, 10, v4
	v_lshlrev_b32_e32 v5, 6, v8
	v_add_u32_e32 v8, s34, v8
	v_mul_u32_u24_e32 v4, 0x90, v3
	v_ashrrev_i32_e32 v9, 31, v8
	s_ashr_i32 s31, s30, 31
	v_add3_u32 v4, v4, v5, v152
	v_lshlrev_b64 v[8:9], 16, v[8:9]
	s_lshl_b64 s[4:5], s[30:31], 8
	ds_read_b128 v[4:7], v4 offset:36864
	v_lshl_add_u64 v[8:9], v[8:9], 0, s[4:5]
	v_or_b32_e32 v8, v8, v3
	v_lshlrev_b64 v[8:9], 6, v[8:9]
	v_lshl_add_u64 v[8:9], s[8:9], 0, v[8:9]
	v_lshl_add_u64 v[8:9], v[8:9], 0, v[152:153]
	s_waitcnt lgkmcnt(0)
	global_store_dwordx4 v[8:9], v[4:7], off nt
.LBB0_966:
	s_or_b64 exec, exec, s[6:7]
	s_and_saveexec_b64 s[4:5], vcc
	s_cbranch_execz .LBB0_968
	v_add_u32_e32 v3, 0x400, v0
	v_ashrrev_i32_e32 v6, 10, v3
	v_lshlrev_b32_e32 v3, 6, v6
	v_add_u32_e32 v6, s34, v6
	v_ashrrev_i32_e32 v7, 31, v6
	s_ashr_i32 s31, s30, 31
	v_add3_u32 v2, v2, v3, v152
	v_lshlrev_b64 v[6:7], 16, v[6:7]
	s_lshl_b64 s[6:7], s[30:31], 8
	ds_read_b128 v[2:5], v2 offset:36864
	v_lshl_add_u64 v[6:7], v[6:7], 0, s[6:7]
	v_or_b32_e32 v6, v6, v1
	v_lshlrev_b64 v[6:7], 6, v[6:7]
	v_lshl_add_u64 v[6:7], s[8:9], 0, v[6:7]
	v_lshl_add_u64 v[6:7], v[6:7], 0, v[152:153]
	s_waitcnt lgkmcnt(0)
	global_store_dwordx4 v[6:7], v[2:5], off nt
.LBB0_968:
	s_or_b64 exec, exec, s[4:5]
	s_nop 0
	v_add_u32_e32 v2, 0x500, v0
	v_bfe_u32 v1, v2, 2, 8
	v_cmp_lt_u32_e32 vcc, 1, v1
	s_and_saveexec_b64 s[4:5], vcc
	s_cbranch_execz .LBB0_970
	v_ashrrev_i32_e32 v6, 10, v2
	v_lshlrev_b32_e32 v3, 6, v6
	v_add_u32_e32 v6, s34, v6
	v_mul_u32_u24_e32 v2, 0x90, v1
	v_ashrrev_i32_e32 v7, 31, v6
	s_ashr_i32 s31, s30, 31
	v_add3_u32 v2, v2, v3, v152
	v_lshlrev_b64 v[6:7], 16, v[6:7]
	s_lshl_b64 s[6:7], s[30:31], 8
	ds_read_b128 v[2:5], v2 offset:36864
	v_lshl_add_u64 v[6:7], v[6:7], 0, s[6:7]
	v_or_b32_e32 v6, v6, v1
	v_lshlrev_b64 v[6:7], 6, v[6:7]
	v_lshl_add_u64 v[6:7], s[8:9], 0, v[6:7]
	v_lshl_add_u64 v[6:7], v[6:7], 0, v[152:153]
	s_waitcnt lgkmcnt(0)
	global_store_dwordx4 v[6:7], v[2:5], off nt
.LBB0_970:
	s_or_b64 exec, exec, s[4:5]
	s_nop 0
	v_add_u32_e32 v2, 0x600, v0
	v_bfe_u32 v1, v2, 2, 8
	v_cmp_lt_u32_e32 vcc, 1, v1
	s_and_saveexec_b64 s[4:5], vcc
	s_cbranch_execz .LBB0_972
	v_ashrrev_i32_e32 v6, 10, v2
	v_lshlrev_b32_e32 v3, 6, v6
	v_add_u32_e32 v6, s34, v6
	v_mul_u32_u24_e32 v2, 0x90, v1
	v_ashrrev_i32_e32 v7, 31, v6
	s_ashr_i32 s31, s30, 31
	v_add3_u32 v2, v2, v3, v152
	v_lshlrev_b64 v[6:7], 16, v[6:7]
	s_lshl_b64 s[6:7], s[30:31], 8
	ds_read_b128 v[2:5], v2 offset:36864
	v_lshl_add_u64 v[6:7], v[6:7], 0, s[6:7]
	v_or_b32_e32 v6, v6, v1
	v_lshlrev_b64 v[6:7], 6, v[6:7]
	v_lshl_add_u64 v[6:7], s[8:9], 0, v[6:7]
	v_lshl_add_u64 v[6:7], v[6:7], 0, v[152:153]
	s_waitcnt lgkmcnt(0)
	global_store_dwordx4 v[6:7], v[2:5], off nt
.LBB0_972:
	s_or_b64 exec, exec, s[4:5]
	v_add_u32_e32 v1, 0x700, v0
	v_bfe_u32 v0, v1, 2, 8
	v_cmp_lt_u32_e32 vcc, 1, v0
	s_and_saveexec_b64 s[4:5], vcc
	s_cbranch_execz .LBB0_943
	v_ashrrev_i32_e32 v1, 10, v1
	v_add_u32_e32 v6, s34, v1
	v_mul_u32_u24_e32 v2, 0x90, v0
	v_lshlrev_b32_e32 v3, 6, v1
	v_ashrrev_i32_e32 v7, 31, v6
	s_ashr_i32 s31, s30, 31
	v_add3_u32 v2, v2, v3, v152
	v_lshlrev_b64 v[6:7], 16, v[6:7]
	s_lshl_b64 s[6:7], s[30:31], 8
	ds_read_b128 v[2:5], v2 offset:36864
	v_lshl_add_u64 v[6:7], v[6:7], 0, s[6:7]
	v_or_b32_e32 v6, v6, v0
	v_lshlrev_b64 v[0:1], 6, v[6:7]
	v_lshl_add_u64 v[0:1], s[8:9], 0, v[0:1]
	v_lshl_add_u64 v[0:1], v[0:1], 0, v[152:153]
	s_waitcnt lgkmcnt(0)
	global_store_dwordx4 v[0:1], v[2:5], off nt
	s_branch .LBB0_943
